# grid barriers fully flat: every workgroup polls TOP >= K*nXCD itself (no per-XCD release word), leader invalidate issued right after its TOP add, XGEN bump dropped
# speedup vs baseline: 1.0033x; 1.0033x over previous
; DI unsigned xb_ld(unsigned* p)              { return __hip_atomic_load(p, __ATOMIC_RELAXED, __HIP_MEMORY_SCOPE_AGENT); }
; DI unsigned xb_add(unsigned* p, unsigned v) { return __hip_atomic_fetch_add(p, v, __ATOMIC_RELAXED, __HIP_MEMORY_SCOPE_AGENT); }
; #define XB_SPIN(cond, bar) do { unsigned _sp = 0; while (cond) { __builtin_amdgcn_s_sleep(1); \
;     if ((++_sp & 255u) == 0u) { if (xb_ld(&(bar)[XB_TMO])) break; if (_sp > XB_SPIN_CAP) { atomicAdd(&(bar)[XB_TMO], 1u); break; } } } } while (0)
; DI void xcd_barrier(unsigned* bar, volatile __attribute__((address_space(3))) unsigned* st) {
;     ...
;         const unsigned old = xb_add(&bar[XB_XSUB(x)], 1u);
;         const unsigned gen = old / nloc;
;         if (old + 1u == (gen + 1u) * nloc) {
;             __builtin_amdgcn_fence(__ATOMIC_RELEASE, "agent");
;             asm volatile("s_waitcnt vmcnt(0)" ::: "memory");
;             const unsigned og = xb_add(&bar[XB_TOP], 1u);
;             const unsigned tg = og / nx;
;             if (og + 1u == (tg + 1u) * nx) xb_add(&bar[XB_TOPGEN], 1u);
;             else XB_SPIN(xb_ld(&bar[XB_TOPGEN]) == tg, bar);
;             __builtin_amdgcn_fence(__ATOMIC_ACQUIRE, "agent");
;             xb_add(&bar[XB_XGEN(x)], 1u);
;             asm volatile("s_waitcnt vmcnt(0)" ::: "memory");
;         } else {
;             XB_SPIN(xb_ld(&bar[XB_XGEN(x)]) == gen, bar);
;             __builtin_amdgcn_fence(__ATOMIC_ACQUIRE, "agent");
.LBB0_150:
	s_or_b64 exec, exec, s[8:9]
	v_cvt_f32_u32_e32 v4, v2
	s_waitcnt vmcnt(0)
	v_readfirstlane_b32 s3, v3
	v_sub_u32_e32 v3, 0, v2
	v_rcp_iflag_f32_e32 v4, v4
	v_add_u32_e32 v5, s3, v0
	v_mul_f32_e32 v4, 0x4f7ffffe, v4
	v_cvt_u32_f32_e32 v4, v4
	v_mul_lo_u32 v0, v3, v4
	v_mul_hi_u32 v0, v4, v0
	v_add_u32_e32 v0, v4, v0
	v_mul_hi_u32 v0, v5, v0
	v_mul_lo_u32 v3, v0, v2
	v_sub_u32_e32 v3, v5, v3
	v_add_u32_e32 v4, 1, v0
	v_cmp_ge_u32_e32 vcc, v3, v2
	s_nop 1
	v_cndmask_b32_e32 v0, v0, v4, vcc
	v_sub_u32_e32 v4, v3, v2
	v_cndmask_b32_e32 v3, v3, v4, vcc
	v_add_u32_e32 v4, 1, v0
	v_cmp_ge_u32_e32 vcc, v3, v2
	v_add_u32_e32 v3, 1, v5
	s_nop 0
	v_cndmask_b32_e32 v0, v0, v4, vcc
	v_mul_lo_u32 v4, v2, v0
	v_add_u32_e32 v2, v4, v2
	v_cmp_ne_u32_e32 vcc, v3, v2
	s_and_saveexec_b64 s[6:7], vcc
	s_xor_b64 s[6:7], exec, s[6:7]
	s_cbranch_execz .LBB0_164
	buffer_inv sc1
	s_waitcnt lgkmcnt(0)
	v_mul_u32_u24_e32 v4, 1, v1
	v_mov_b32_e32 v2, 0x34e5000

; DI unsigned xb_ld(unsigned* p)              { return __hip_atomic_load(p, __ATOMIC_RELAXED, __HIP_MEMORY_SCOPE_AGENT); }
; DI unsigned xb_add(unsigned* p, unsigned v) { return __hip_atomic_fetch_add(p, v, __ATOMIC_RELAXED, __HIP_MEMORY_SCOPE_AGENT); }
; #define XB_SPIN(cond, bar) do { unsigned _sp = 0; while (cond) { __builtin_amdgcn_s_sleep(1); \
;     if ((++_sp & 255u) == 0u) { if (xb_ld(&(bar)[XB_TMO])) break; if (_sp > XB_SPIN_CAP) { atomicAdd(&(bar)[XB_TMO], 1u); break; } } } } while (0)
; DI void xcd_barrier(unsigned* bar, volatile __attribute__((address_space(3))) unsigned* st) {
;     ...
;             __builtin_amdgcn_fence(__ATOMIC_RELEASE, "agent");
;             asm volatile("s_waitcnt vmcnt(0)" ::: "memory");
;             const unsigned og = xb_add(&bar[XB_TOP], 1u);
;             const unsigned tg = og / nx;
;             if (og + 1u == (tg + 1u) * nx) xb_add(&bar[XB_TOPGEN], 1u);
;             else XB_SPIN(xb_ld(&bar[XB_TOPGEN]) == tg, bar);
;             __builtin_amdgcn_fence(__ATOMIC_ACQUIRE, "agent");
;             xb_add(&bar[XB_XGEN(x)], 1u);
;             asm volatile("s_waitcnt vmcnt(0)" ::: "memory");
;         } else {
;             XB_SPIN(xb_ld(&bar[XB_XGEN(x)]) == gen, bar);
;             __builtin_amdgcn_fence(__ATOMIC_ACQUIRE, "agent");
;             asm volatile("s_waitcnt vmcnt(0)" ::: "memory");
;         }
.Lnlf_d1:
	s_mov_b64 s[8:9], exec
.LBB0_163:
	s_or_b64 exec, exec, s[8:9]
	s_waitcnt vmcnt(0)
	s_waitcnt vmcnt(0)
.LBB0_164:
	s_andn2_saveexec_b64 s[6:7], s[6:7]
	s_cbranch_execz .LBB0_184
	s_mov_b64 s[6:7], exec
	buffer_wbl2 sc1
	s_waitcnt lgkmcnt(0)
	s_waitcnt vmcnt(0)
	v_mov_b32_e32 v2, 0x34e5000
	v_mov_b32_e32 v3, 1
	global_atomic_add v2, v3, s[70:71] offset:1280
	v_mul_u32_u24_e32 v4, 1, v1
	buffer_inv sc1

; DI unsigned xb_add(unsigned* p, unsigned v) { return __hip_atomic_fetch_add(p, v, __ATOMIC_RELAXED, __HIP_MEMORY_SCOPE_AGENT); }
; DI void xcd_barrier(unsigned* bar, volatile __attribute__((address_space(3))) unsigned* st) {
;     ...
;             __builtin_amdgcn_fence(__ATOMIC_ACQUIRE, "agent");
;             xb_add(&bar[XB_XGEN(x)], 1u);
;             asm volatile("s_waitcnt vmcnt(0)" ::: "memory");
.LBB0_181:
	s_or_b64 exec, exec, s[6:7]
	s_mov_b64 s[6:7], exec
	v_mbcnt_lo_u32_b32 v0, s6, 0
	v_mbcnt_hi_u32_b32 v0, s7, v0
	v_cmp_eq_u32_e32 vcc, 0, v0
	s_and_saveexec_b64 s[8:9], vcc
	s_cbranch_execz .LBB0_183

; DI unsigned xb_ld(unsigned* p)              { return __hip_atomic_load(p, __ATOMIC_RELAXED, __HIP_MEMORY_SCOPE_AGENT); }
; DI unsigned xb_add(unsigned* p, unsigned v) { return __hip_atomic_fetch_add(p, v, __ATOMIC_RELAXED, __HIP_MEMORY_SCOPE_AGENT); }
; #define XB_SPIN(cond, bar) do { unsigned _sp = 0; while (cond) { __builtin_amdgcn_s_sleep(1); \
;     if ((++_sp & 255u) == 0u) { if (xb_ld(&(bar)[XB_TMO])) break; if (_sp > XB_SPIN_CAP) { atomicAdd(&(bar)[XB_TMO], 1u); break; } } } } while (0)
; DI void xcd_barrier(unsigned* bar, volatile __attribute__((address_space(3))) unsigned* st) {
;     ...
;         const unsigned old = xb_add(&bar[XB_XSUB(x)], 1u);
;         const unsigned gen = old / nloc;
;         if (old + 1u == (gen + 1u) * nloc) {
;             __builtin_amdgcn_fence(__ATOMIC_RELEASE, "agent");
;             asm volatile("s_waitcnt vmcnt(0)" ::: "memory");
;             const unsigned og = xb_add(&bar[XB_TOP], 1u);
;             const unsigned tg = og / nx;
;             if (og + 1u == (tg + 1u) * nx) xb_add(&bar[XB_TOPGEN], 1u);
;             else XB_SPIN(xb_ld(&bar[XB_TOPGEN]) == tg, bar);
;             __builtin_amdgcn_fence(__ATOMIC_ACQUIRE, "agent");
;             xb_add(&bar[XB_XGEN(x)], 1u);
;             asm volatile("s_waitcnt vmcnt(0)" ::: "memory");
;         } else {
;             XB_SPIN(xb_ld(&bar[XB_XGEN(x)]) == gen, bar);
;             __builtin_amdgcn_fence(__ATOMIC_ACQUIRE, "agent");
.LBB0_240:
	s_or_b64 exec, exec, s[10:11]
	v_cvt_f32_u32_e32 v4, v2
	s_waitcnt vmcnt(0)
	v_readfirstlane_b32 s3, v3
	v_sub_u32_e32 v3, 0, v2
	v_rcp_iflag_f32_e32 v4, v4
	v_add_u32_e32 v5, s3, v0
	v_mul_f32_e32 v4, 0x4f7ffffe, v4
	v_cvt_u32_f32_e32 v4, v4
	v_mul_lo_u32 v0, v3, v4
	v_mul_hi_u32 v0, v4, v0
	v_add_u32_e32 v0, v4, v0
	v_mul_hi_u32 v0, v5, v0
	v_mul_lo_u32 v3, v0, v2
	v_sub_u32_e32 v3, v5, v3
	v_add_u32_e32 v4, 1, v0
	v_cmp_ge_u32_e32 vcc, v3, v2
	s_nop 1
	v_cndmask_b32_e32 v0, v0, v4, vcc
	v_sub_u32_e32 v4, v3, v2
	v_cndmask_b32_e32 v3, v3, v4, vcc
	v_add_u32_e32 v4, 1, v0
	v_cmp_ge_u32_e32 vcc, v3, v2
	v_add_u32_e32 v3, 1, v5
	s_nop 0
	v_cndmask_b32_e32 v0, v0, v4, vcc
	v_mul_lo_u32 v4, v2, v0
	v_add_u32_e32 v2, v4, v2
	v_cmp_ne_u32_e32 vcc, v3, v2
	s_and_saveexec_b64 s[8:9], vcc
	s_xor_b64 s[8:9], exec, s[8:9]
	s_cbranch_execz .LBB0_254
	buffer_inv sc1
	s_waitcnt lgkmcnt(0)
	v_mul_u32_u24_e32 v4, 2, v1
	v_mov_b32_e32 v2, 0x34e5000

; DI unsigned xb_ld(unsigned* p)              { return __hip_atomic_load(p, __ATOMIC_RELAXED, __HIP_MEMORY_SCOPE_AGENT); }
; #define XB_SPIN(cond, bar) do { unsigned _sp = 0; while (cond) { __builtin_amdgcn_s_sleep(1); \
;     if ((++_sp & 255u) == 0u) { if (xb_ld(&(bar)[XB_TMO])) break; if (_sp > XB_SPIN_CAP) { atomicAdd(&(bar)[XB_TMO], 1u); break; } } } } while (0)
; DI void xcd_barrier(unsigned* bar, volatile __attribute__((address_space(3))) unsigned* st) {
;     ...
;             XB_SPIN(xb_ld(&bar[XB_XGEN(x)]) == gen, bar);
;             __builtin_amdgcn_fence(__ATOMIC_ACQUIRE, "agent");
;             asm volatile("s_waitcnt vmcnt(0)" ::: "memory");
;         }
.Lnlf_d2:
	s_mov_b64 s[10:11], exec

; DI unsigned xb_ld(unsigned* p)              { return __hip_atomic_load(p, __ATOMIC_RELAXED, __HIP_MEMORY_SCOPE_AGENT); }
; DI unsigned xb_add(unsigned* p, unsigned v) { return __hip_atomic_fetch_add(p, v, __ATOMIC_RELAXED, __HIP_MEMORY_SCOPE_AGENT); }
; #define XB_SPIN(cond, bar) do { unsigned _sp = 0; while (cond) { __builtin_amdgcn_s_sleep(1); \
;     if ((++_sp & 255u) == 0u) { if (xb_ld(&(bar)[XB_TMO])) break; if (_sp > XB_SPIN_CAP) { atomicAdd(&(bar)[XB_TMO], 1u); break; } } } } while (0)
; DI void xcd_barrier(unsigned* bar, volatile __attribute__((address_space(3))) unsigned* st) {
;     ...
;             __builtin_amdgcn_fence(__ATOMIC_RELEASE, "agent");
;             asm volatile("s_waitcnt vmcnt(0)" ::: "memory");
;             const unsigned og = xb_add(&bar[XB_TOP], 1u);
;             const unsigned tg = og / nx;
;             if (og + 1u == (tg + 1u) * nx) xb_add(&bar[XB_TOPGEN], 1u);
;             else XB_SPIN(xb_ld(&bar[XB_TOPGEN]) == tg, bar);
;             __builtin_amdgcn_fence(__ATOMIC_ACQUIRE, "agent");
.LBB0_254:
	s_andn2_saveexec_b64 s[8:9], s[8:9]
	s_cbranch_execz .LBB0_274
	s_mov_b64 s[8:9], exec
	buffer_wbl2 sc1
	s_waitcnt lgkmcnt(0)
	s_waitcnt vmcnt(0)
	v_mov_b32_e32 v2, 0x34e5000
	v_mov_b32_e32 v3, 1
	global_atomic_add v2, v3, s[70:71] offset:1280
	v_mul_u32_u24_e32 v4, 2, v1
	buffer_inv sc1

; DI unsigned xb_add(unsigned* p, unsigned v) { return __hip_atomic_fetch_add(p, v, __ATOMIC_RELAXED, __HIP_MEMORY_SCOPE_AGENT); }
; DI void xcd_barrier(unsigned* bar, volatile __attribute__((address_space(3))) unsigned* st) {
;     ...
;             __builtin_amdgcn_fence(__ATOMIC_ACQUIRE, "agent");
;             xb_add(&bar[XB_XGEN(x)], 1u);
;             asm volatile("s_waitcnt vmcnt(0)" ::: "memory");
.LBB0_271:
	s_or_b64 exec, exec, s[8:9]
	s_mov_b64 s[8:9], exec
	v_mbcnt_lo_u32_b32 v0, s8, 0
	v_mbcnt_hi_u32_b32 v0, s9, v0
	v_cmp_eq_u32_e32 vcc, 0, v0
	s_and_saveexec_b64 s[10:11], vcc
	s_cbranch_execz .LBB0_273

; DI unsigned xb_ld(unsigned* p)              { return __hip_atomic_load(p, __ATOMIC_RELAXED, __HIP_MEMORY_SCOPE_AGENT); }
; DI unsigned xb_add(unsigned* p, unsigned v) { return __hip_atomic_fetch_add(p, v, __ATOMIC_RELAXED, __HIP_MEMORY_SCOPE_AGENT); }
; #define XB_SPIN(cond, bar) do { unsigned _sp = 0; while (cond) { __builtin_amdgcn_s_sleep(1); \
;     if ((++_sp & 255u) == 0u) { if (xb_ld(&(bar)[XB_TMO])) break; if (_sp > XB_SPIN_CAP) { atomicAdd(&(bar)[XB_TMO], 1u); break; } } } } while (0)
; DI void xcd_barrier(unsigned* bar, volatile __attribute__((address_space(3))) unsigned* st) {
;     ...
;         const unsigned old = xb_add(&bar[XB_XSUB(x)], 1u);
;         const unsigned gen = old / nloc;
;         if (old + 1u == (gen + 1u) * nloc) {
;             __builtin_amdgcn_fence(__ATOMIC_RELEASE, "agent");
;             asm volatile("s_waitcnt vmcnt(0)" ::: "memory");
;             const unsigned og = xb_add(&bar[XB_TOP], 1u);
;             const unsigned tg = og / nx;
;             if (og + 1u == (tg + 1u) * nx) xb_add(&bar[XB_TOPGEN], 1u);
;             else XB_SPIN(xb_ld(&bar[XB_TOPGEN]) == tg, bar);
;             __builtin_amdgcn_fence(__ATOMIC_ACQUIRE, "agent");
;             xb_add(&bar[XB_XGEN(x)], 1u);
;             asm volatile("s_waitcnt vmcnt(0)" ::: "memory");
;         } else {
;             XB_SPIN(xb_ld(&bar[XB_XGEN(x)]) == gen, bar);
;             __builtin_amdgcn_fence(__ATOMIC_ACQUIRE, "agent");
.LBB0_323:
	s_or_b64 exec, exec, s[10:11]
	v_cvt_f32_u32_e32 v4, v2
	s_waitcnt vmcnt(0)
	v_readfirstlane_b32 s3, v3
	v_sub_u32_e32 v3, 0, v2
	v_rcp_iflag_f32_e32 v4, v4
	v_add_u32_e32 v5, s3, v0
	v_mul_f32_e32 v4, 0x4f7ffffe, v4
	v_cvt_u32_f32_e32 v4, v4
	v_mul_lo_u32 v0, v3, v4
	v_mul_hi_u32 v0, v4, v0
	v_add_u32_e32 v0, v4, v0
	v_mul_hi_u32 v0, v5, v0
	v_mul_lo_u32 v3, v0, v2
	v_sub_u32_e32 v3, v5, v3
	v_add_u32_e32 v4, 1, v0
	v_cmp_ge_u32_e32 vcc, v3, v2
	s_nop 1
	v_cndmask_b32_e32 v0, v0, v4, vcc
	v_sub_u32_e32 v4, v3, v2
	v_cndmask_b32_e32 v3, v3, v4, vcc
	v_add_u32_e32 v4, 1, v0
	v_cmp_ge_u32_e32 vcc, v3, v2
	v_add_u32_e32 v3, 1, v5
	s_nop 0
	v_cndmask_b32_e32 v0, v0, v4, vcc
	v_mul_lo_u32 v4, v2, v0
	v_add_u32_e32 v2, v4, v2
	v_cmp_ne_u32_e32 vcc, v3, v2
	s_and_saveexec_b64 s[8:9], vcc
	s_xor_b64 s[8:9], exec, s[8:9]
	s_cbranch_execz .LBB0_337
	buffer_inv sc1
	s_waitcnt lgkmcnt(0)
	v_mul_u32_u24_e32 v4, 3, v1
	v_mov_b32_e32 v2, 0x34e5000

; DI unsigned xb_ld(unsigned* p)              { return __hip_atomic_load(p, __ATOMIC_RELAXED, __HIP_MEMORY_SCOPE_AGENT); }
; DI unsigned xb_add(unsigned* p, unsigned v) { return __hip_atomic_fetch_add(p, v, __ATOMIC_RELAXED, __HIP_MEMORY_SCOPE_AGENT); }
; #define XB_SPIN(cond, bar) do { unsigned _sp = 0; while (cond) { __builtin_amdgcn_s_sleep(1); \
;     if ((++_sp & 255u) == 0u) { if (xb_ld(&(bar)[XB_TMO])) break; if (_sp > XB_SPIN_CAP) { atomicAdd(&(bar)[XB_TMO], 1u); break; } } } } while (0)
; DI void xcd_barrier(unsigned* bar, volatile __attribute__((address_space(3))) unsigned* st) {
;     ...
;             __builtin_amdgcn_fence(__ATOMIC_RELEASE, "agent");
;             asm volatile("s_waitcnt vmcnt(0)" ::: "memory");
;             const unsigned og = xb_add(&bar[XB_TOP], 1u);
;             const unsigned tg = og / nx;
;             if (og + 1u == (tg + 1u) * nx) xb_add(&bar[XB_TOPGEN], 1u);
;             else XB_SPIN(xb_ld(&bar[XB_TOPGEN]) == tg, bar);
;             __builtin_amdgcn_fence(__ATOMIC_ACQUIRE, "agent");
.LBB0_337:
	s_andn2_saveexec_b64 s[8:9], s[8:9]
	s_cbranch_execz .LBB0_357
	s_mov_b64 s[8:9], exec
	buffer_wbl2 sc1
	s_waitcnt lgkmcnt(0)
	s_waitcnt vmcnt(0)
	v_mov_b32_e32 v2, 0x34e5000
	v_mov_b32_e32 v3, 1
	global_atomic_add v2, v3, s[70:71] offset:1280
	v_mul_u32_u24_e32 v4, 3, v1
	buffer_inv sc1

; DI unsigned xb_ld(unsigned* p)              { return __hip_atomic_load(p, __ATOMIC_RELAXED, __HIP_MEMORY_SCOPE_AGENT); }
; DI unsigned xb_add(unsigned* p, unsigned v) { return __hip_atomic_fetch_add(p, v, __ATOMIC_RELAXED, __HIP_MEMORY_SCOPE_AGENT); }
; #define XB_SPIN(cond, bar) do { unsigned _sp = 0; while (cond) { __builtin_amdgcn_s_sleep(1); \
;     if ((++_sp & 255u) == 0u) { if (xb_ld(&(bar)[XB_TMO])) break; if (_sp > XB_SPIN_CAP) { atomicAdd(&(bar)[XB_TMO], 1u); break; } } } } while (0)
; DI void xcd_barrier(unsigned* bar, volatile __attribute__((address_space(3))) unsigned* st) {
;     ...
;         const unsigned old = xb_add(&bar[XB_XSUB(x)], 1u);
;         const unsigned gen = old / nloc;
;         if (old + 1u == (gen + 1u) * nloc) {
;             __builtin_amdgcn_fence(__ATOMIC_RELEASE, "agent");
;             asm volatile("s_waitcnt vmcnt(0)" ::: "memory");
;             const unsigned og = xb_add(&bar[XB_TOP], 1u);
;             const unsigned tg = og / nx;
;             if (og + 1u == (tg + 1u) * nx) xb_add(&bar[XB_TOPGEN], 1u);
;             else XB_SPIN(xb_ld(&bar[XB_TOPGEN]) == tg, bar);
;             __builtin_amdgcn_fence(__ATOMIC_ACQUIRE, "agent");
;             xb_add(&bar[XB_XGEN(x)], 1u);
;             asm volatile("s_waitcnt vmcnt(0)" ::: "memory");
;         } else {
;             XB_SPIN(xb_ld(&bar[XB_XGEN(x)]) == gen, bar);
;             __builtin_amdgcn_fence(__ATOMIC_ACQUIRE, "agent");
.LBB0_400:
	s_or_b64 exec, exec, s[8:9]
	v_cvt_f32_u32_e32 v4, v2
	s_waitcnt vmcnt(0)
	v_readfirstlane_b32 s3, v3
	v_sub_u32_e32 v3, 0, v2
	v_rcp_iflag_f32_e32 v4, v4
	v_add_u32_e32 v5, s3, v0
	v_mul_f32_e32 v4, 0x4f7ffffe, v4
	v_cvt_u32_f32_e32 v4, v4
	v_mul_lo_u32 v0, v3, v4
	v_mul_hi_u32 v0, v4, v0
	v_add_u32_e32 v0, v4, v0
	v_mul_hi_u32 v0, v5, v0
	v_mul_lo_u32 v3, v0, v2
	v_sub_u32_e32 v3, v5, v3
	v_add_u32_e32 v4, 1, v0
	v_cmp_ge_u32_e32 vcc, v3, v2
	s_nop 1
	v_cndmask_b32_e32 v0, v0, v4, vcc
	v_sub_u32_e32 v4, v3, v2
	v_cndmask_b32_e32 v3, v3, v4, vcc
	v_add_u32_e32 v4, 1, v0
	v_cmp_ge_u32_e32 vcc, v3, v2
	v_add_u32_e32 v3, 1, v5
	s_nop 0
	v_cndmask_b32_e32 v0, v0, v4, vcc
	v_mul_lo_u32 v4, v2, v0
	v_add_u32_e32 v2, v4, v2
	v_cmp_ne_u32_e32 vcc, v3, v2
	s_and_saveexec_b64 s[6:7], vcc
	s_xor_b64 s[6:7], exec, s[6:7]
	s_cbranch_execz .LBB0_414
	buffer_inv sc1
	s_waitcnt lgkmcnt(0)
	v_mul_u32_u24_e32 v4, 4, v1
	v_mov_b32_e32 v2, 0x34e5000

; DI unsigned xb_ld(unsigned* p)              { return __hip_atomic_load(p, __ATOMIC_RELAXED, __HIP_MEMORY_SCOPE_AGENT); }
; DI unsigned xb_add(unsigned* p, unsigned v) { return __hip_atomic_fetch_add(p, v, __ATOMIC_RELAXED, __HIP_MEMORY_SCOPE_AGENT); }
; #define XB_SPIN(cond, bar) do { unsigned _sp = 0; while (cond) { __builtin_amdgcn_s_sleep(1); \
;     if ((++_sp & 255u) == 0u) { if (xb_ld(&(bar)[XB_TMO])) break; if (_sp > XB_SPIN_CAP) { atomicAdd(&(bar)[XB_TMO], 1u); break; } } } } while (0)
; DI void xcd_barrier(unsigned* bar, volatile __attribute__((address_space(3))) unsigned* st) {
;     ...
;             __builtin_amdgcn_fence(__ATOMIC_RELEASE, "agent");
;             asm volatile("s_waitcnt vmcnt(0)" ::: "memory");
;             const unsigned og = xb_add(&bar[XB_TOP], 1u);
;             const unsigned tg = og / nx;
;             if (og + 1u == (tg + 1u) * nx) xb_add(&bar[XB_TOPGEN], 1u);
;             else XB_SPIN(xb_ld(&bar[XB_TOPGEN]) == tg, bar);
;             __builtin_amdgcn_fence(__ATOMIC_ACQUIRE, "agent");
;             xb_add(&bar[XB_XGEN(x)], 1u);
;             asm volatile("s_waitcnt vmcnt(0)" ::: "memory");
;         } else {
;             XB_SPIN(xb_ld(&bar[XB_XGEN(x)]) == gen, bar);
;             __builtin_amdgcn_fence(__ATOMIC_ACQUIRE, "agent");
;             asm volatile("s_waitcnt vmcnt(0)" ::: "memory");
;         }
.Lnlf_d4:
	s_mov_b64 s[8:9], exec
.LBB0_413:
	s_or_b64 exec, exec, s[8:9]
	s_waitcnt vmcnt(0)
	s_waitcnt vmcnt(0)
.LBB0_414:
	s_andn2_saveexec_b64 s[6:7], s[6:7]
	s_cbranch_execz .LBB0_434
	s_mov_b64 s[6:7], exec
	buffer_wbl2 sc1
	s_waitcnt lgkmcnt(0)
	s_waitcnt vmcnt(0)
	v_mov_b32_e32 v2, 0x34e5000
	v_mov_b32_e32 v3, 1
	global_atomic_add v2, v3, s[70:71] offset:1280
	v_mul_u32_u24_e32 v4, 4, v1
	buffer_inv sc1

; DI unsigned xb_ld(unsigned* p)              { return __hip_atomic_load(p, __ATOMIC_RELAXED, __HIP_MEMORY_SCOPE_AGENT); }
; DI unsigned xb_add(unsigned* p, unsigned v) { return __hip_atomic_fetch_add(p, v, __ATOMIC_RELAXED, __HIP_MEMORY_SCOPE_AGENT); }
; #define XB_SPIN(cond, bar) do { unsigned _sp = 0; while (cond) { __builtin_amdgcn_s_sleep(1); \
;     if ((++_sp & 255u) == 0u) { if (xb_ld(&(bar)[XB_TMO])) break; if (_sp > XB_SPIN_CAP) { atomicAdd(&(bar)[XB_TMO], 1u); break; } } } } while (0)
; DI void xcd_barrier(unsigned* bar, volatile __attribute__((address_space(3))) unsigned* st) {
;     ...
;         const unsigned old = xb_add(&bar[XB_XSUB(x)], 1u);
;         const unsigned gen = old / nloc;
;         if (old + 1u == (gen + 1u) * nloc) {
;             __builtin_amdgcn_fence(__ATOMIC_RELEASE, "agent");
;             asm volatile("s_waitcnt vmcnt(0)" ::: "memory");
;             const unsigned og = xb_add(&bar[XB_TOP], 1u);
;             const unsigned tg = og / nx;
;             if (og + 1u == (tg + 1u) * nx) xb_add(&bar[XB_TOPGEN], 1u);
;             else XB_SPIN(xb_ld(&bar[XB_TOPGEN]) == tg, bar);
;             __builtin_amdgcn_fence(__ATOMIC_ACQUIRE, "agent");
;             xb_add(&bar[XB_XGEN(x)], 1u);
;             asm volatile("s_waitcnt vmcnt(0)" ::: "memory");
;         } else {
;             XB_SPIN(xb_ld(&bar[XB_XGEN(x)]) == gen, bar);
;             __builtin_amdgcn_fence(__ATOMIC_ACQUIRE, "agent");
.LBB0_490:
	s_or_b64 exec, exec, s[10:11]
	v_cvt_f32_u32_e32 v4, v2
	s_waitcnt vmcnt(0)
	v_readfirstlane_b32 s3, v3
	v_sub_u32_e32 v3, 0, v2
	v_rcp_iflag_f32_e32 v4, v4
	v_add_u32_e32 v5, s3, v0
	v_mul_f32_e32 v4, 0x4f7ffffe, v4
	v_cvt_u32_f32_e32 v4, v4
	v_mul_lo_u32 v0, v3, v4
	v_mul_hi_u32 v0, v4, v0
	v_add_u32_e32 v0, v4, v0
	v_mul_hi_u32 v0, v5, v0
	v_mul_lo_u32 v3, v0, v2
	v_sub_u32_e32 v3, v5, v3
	v_add_u32_e32 v4, 1, v0
	v_cmp_ge_u32_e32 vcc, v3, v2
	s_nop 1
	v_cndmask_b32_e32 v0, v0, v4, vcc
	v_sub_u32_e32 v4, v3, v2
	v_cndmask_b32_e32 v3, v3, v4, vcc
	v_add_u32_e32 v4, 1, v0
	v_cmp_ge_u32_e32 vcc, v3, v2
	v_add_u32_e32 v3, 1, v5
	s_nop 0
	v_cndmask_b32_e32 v0, v0, v4, vcc
	v_mul_lo_u32 v4, v2, v0
	v_add_u32_e32 v2, v4, v2
	v_cmp_ne_u32_e32 vcc, v3, v2
	s_and_saveexec_b64 s[8:9], vcc
	s_xor_b64 s[8:9], exec, s[8:9]
	s_cbranch_execz .LBB0_504
	buffer_inv sc1
	s_waitcnt lgkmcnt(0)
	v_mul_u32_u24_e32 v4, 5, v1
	v_mov_b32_e32 v2, 0x34e5000

; DI unsigned xb_ld(unsigned* p)              { return __hip_atomic_load(p, __ATOMIC_RELAXED, __HIP_MEMORY_SCOPE_AGENT); }
; DI unsigned xb_add(unsigned* p, unsigned v) { return __hip_atomic_fetch_add(p, v, __ATOMIC_RELAXED, __HIP_MEMORY_SCOPE_AGENT); }
; #define XB_SPIN(cond, bar) do { unsigned _sp = 0; while (cond) { __builtin_amdgcn_s_sleep(1); \
;     if ((++_sp & 255u) == 0u) { if (xb_ld(&(bar)[XB_TMO])) break; if (_sp > XB_SPIN_CAP) { atomicAdd(&(bar)[XB_TMO], 1u); break; } } } } while (0)
; DI void xcd_barrier(unsigned* bar, volatile __attribute__((address_space(3))) unsigned* st) {
;     ...
;             __builtin_amdgcn_fence(__ATOMIC_RELEASE, "agent");
;             asm volatile("s_waitcnt vmcnt(0)" ::: "memory");
;             const unsigned og = xb_add(&bar[XB_TOP], 1u);
;             const unsigned tg = og / nx;
;             if (og + 1u == (tg + 1u) * nx) xb_add(&bar[XB_TOPGEN], 1u);
;             else XB_SPIN(xb_ld(&bar[XB_TOPGEN]) == tg, bar);
;             __builtin_amdgcn_fence(__ATOMIC_ACQUIRE, "agent");
.LBB0_504:
	s_andn2_saveexec_b64 s[8:9], s[8:9]
	s_cbranch_execz .LBB0_524
	s_mov_b64 s[8:9], exec
	buffer_wbl2 sc1
	s_waitcnt lgkmcnt(0)
	s_waitcnt vmcnt(0)
	v_mov_b32_e32 v2, 0x34e5000
	v_mov_b32_e32 v3, 1
	global_atomic_add v2, v3, s[70:71] offset:1280
	v_mul_u32_u24_e32 v4, 5, v1
	buffer_inv sc1

; DI unsigned xb_ld(unsigned* p)              { return __hip_atomic_load(p, __ATOMIC_RELAXED, __HIP_MEMORY_SCOPE_AGENT); }
; DI unsigned xb_add(unsigned* p, unsigned v) { return __hip_atomic_fetch_add(p, v, __ATOMIC_RELAXED, __HIP_MEMORY_SCOPE_AGENT); }
; #define XB_SPIN(cond, bar) do { unsigned _sp = 0; while (cond) { __builtin_amdgcn_s_sleep(1); \
;     if ((++_sp & 255u) == 0u) { if (xb_ld(&(bar)[XB_TMO])) break; if (_sp > XB_SPIN_CAP) { atomicAdd(&(bar)[XB_TMO], 1u); break; } } } } while (0)
; DI void xcd_barrier(unsigned* bar, volatile __attribute__((address_space(3))) unsigned* st) {
;     ...
;         const unsigned old = xb_add(&bar[XB_XSUB(x)], 1u);
;         const unsigned gen = old / nloc;
;         if (old + 1u == (gen + 1u) * nloc) {
;             __builtin_amdgcn_fence(__ATOMIC_RELEASE, "agent");
;             asm volatile("s_waitcnt vmcnt(0)" ::: "memory");
;             const unsigned og = xb_add(&bar[XB_TOP], 1u);
;             const unsigned tg = og / nx;
;             if (og + 1u == (tg + 1u) * nx) xb_add(&bar[XB_TOPGEN], 1u);
;             else XB_SPIN(xb_ld(&bar[XB_TOPGEN]) == tg, bar);
;             __builtin_amdgcn_fence(__ATOMIC_ACQUIRE, "agent");
;             xb_add(&bar[XB_XGEN(x)], 1u);
;             asm volatile("s_waitcnt vmcnt(0)" ::: "memory");
;         } else {
;             XB_SPIN(xb_ld(&bar[XB_XGEN(x)]) == gen, bar);
;             __builtin_amdgcn_fence(__ATOMIC_ACQUIRE, "agent");
.LBB0_598:
	s_or_b64 exec, exec, s[8:9]
	v_cvt_f32_u32_e32 v4, v2
	s_waitcnt vmcnt(0)
	v_readfirstlane_b32 s3, v3
	v_sub_u32_e32 v3, 0, v2
	v_rcp_iflag_f32_e32 v4, v4
	v_add_u32_e32 v5, s3, v0
	v_mul_f32_e32 v4, 0x4f7ffffe, v4
	v_cvt_u32_f32_e32 v4, v4
	v_mul_lo_u32 v0, v3, v4
	v_mul_hi_u32 v0, v4, v0
	v_add_u32_e32 v0, v4, v0
	v_mul_hi_u32 v0, v5, v0
	v_mul_lo_u32 v3, v0, v2
	v_sub_u32_e32 v3, v5, v3
	v_add_u32_e32 v4, 1, v0
	v_cmp_ge_u32_e32 vcc, v3, v2
	s_nop 1
	v_cndmask_b32_e32 v0, v0, v4, vcc
	v_sub_u32_e32 v4, v3, v2
	v_cndmask_b32_e32 v3, v3, v4, vcc
	v_add_u32_e32 v4, 1, v0
	v_cmp_ge_u32_e32 vcc, v3, v2
	v_add_u32_e32 v3, 1, v5
	s_nop 0
	v_cndmask_b32_e32 v0, v0, v4, vcc
	v_mul_lo_u32 v4, v2, v0
	v_add_u32_e32 v2, v4, v2
	v_cmp_ne_u32_e32 vcc, v3, v2
	s_and_saveexec_b64 s[6:7], vcc
	s_xor_b64 s[6:7], exec, s[6:7]
	s_cbranch_execz .LBB0_612
	buffer_inv sc1
	s_waitcnt lgkmcnt(0)
	v_mul_u32_u24_e32 v4, 6, v1
	v_mov_b32_e32 v2, 0x34e5000

; DI unsigned xb_ld(unsigned* p)              { return __hip_atomic_load(p, __ATOMIC_RELAXED, __HIP_MEMORY_SCOPE_AGENT); }
; DI unsigned xb_add(unsigned* p, unsigned v) { return __hip_atomic_fetch_add(p, v, __ATOMIC_RELAXED, __HIP_MEMORY_SCOPE_AGENT); }
; #define XB_SPIN(cond, bar) do { unsigned _sp = 0; while (cond) { __builtin_amdgcn_s_sleep(1); \
;     if ((++_sp & 255u) == 0u) { if (xb_ld(&(bar)[XB_TMO])) break; if (_sp > XB_SPIN_CAP) { atomicAdd(&(bar)[XB_TMO], 1u); break; } } } } while (0)
; DI void xcd_barrier(unsigned* bar, volatile __attribute__((address_space(3))) unsigned* st) {
;     ...
;             __builtin_amdgcn_fence(__ATOMIC_RELEASE, "agent");
;             asm volatile("s_waitcnt vmcnt(0)" ::: "memory");
;             const unsigned og = xb_add(&bar[XB_TOP], 1u);
;             const unsigned tg = og / nx;
;             if (og + 1u == (tg + 1u) * nx) xb_add(&bar[XB_TOPGEN], 1u);
;             else XB_SPIN(xb_ld(&bar[XB_TOPGEN]) == tg, bar);
;             __builtin_amdgcn_fence(__ATOMIC_ACQUIRE, "agent");
;             xb_add(&bar[XB_XGEN(x)], 1u);
;             asm volatile("s_waitcnt vmcnt(0)" ::: "memory");
;         } else {
;             XB_SPIN(xb_ld(&bar[XB_XGEN(x)]) == gen, bar);
;             __builtin_amdgcn_fence(__ATOMIC_ACQUIRE, "agent");
;             asm volatile("s_waitcnt vmcnt(0)" ::: "memory");
;         }
.Lnlf_d6:
	s_mov_b64 s[8:9], exec
.LBB0_611:
	s_or_b64 exec, exec, s[8:9]
	s_waitcnt vmcnt(0)
	s_waitcnt vmcnt(0)
.LBB0_612:
	s_andn2_saveexec_b64 s[6:7], s[6:7]
	s_cbranch_execz .LBB0_632
	s_mov_b64 s[6:7], exec
	buffer_wbl2 sc1
	s_waitcnt lgkmcnt(0)
	s_waitcnt vmcnt(0)
	v_mov_b32_e32 v2, 0x34e5000
	v_mov_b32_e32 v3, 1
	global_atomic_add v2, v3, s[70:71] offset:1280
	v_mul_u32_u24_e32 v4, 6, v1
	buffer_inv sc1

; DI unsigned xb_ld(unsigned* p)              { return __hip_atomic_load(p, __ATOMIC_RELAXED, __HIP_MEMORY_SCOPE_AGENT); }
; DI unsigned xb_add(unsigned* p, unsigned v) { return __hip_atomic_fetch_add(p, v, __ATOMIC_RELAXED, __HIP_MEMORY_SCOPE_AGENT); }
; #define XB_SPIN(cond, bar) do { unsigned _sp = 0; while (cond) { __builtin_amdgcn_s_sleep(1); \
;     if ((++_sp & 255u) == 0u) { if (xb_ld(&(bar)[XB_TMO])) break; if (_sp > XB_SPIN_CAP) { atomicAdd(&(bar)[XB_TMO], 1u); break; } } } } while (0)
; DI void xcd_barrier(unsigned* bar, volatile __attribute__((address_space(3))) unsigned* st) {
;     ...
;         const unsigned old = xb_add(&bar[XB_XSUB(x)], 1u);
;         const unsigned gen = old / nloc;
;         if (old + 1u == (gen + 1u) * nloc) {
;             __builtin_amdgcn_fence(__ATOMIC_RELEASE, "agent");
;             asm volatile("s_waitcnt vmcnt(0)" ::: "memory");
;             const unsigned og = xb_add(&bar[XB_TOP], 1u);
;             const unsigned tg = og / nx;
;             if (og + 1u == (tg + 1u) * nx) xb_add(&bar[XB_TOPGEN], 1u);
;             else XB_SPIN(xb_ld(&bar[XB_TOPGEN]) == tg, bar);
;             __builtin_amdgcn_fence(__ATOMIC_ACQUIRE, "agent");
;             xb_add(&bar[XB_XGEN(x)], 1u);
;             asm volatile("s_waitcnt vmcnt(0)" ::: "memory");
;         } else {
;             XB_SPIN(xb_ld(&bar[XB_XGEN(x)]) == gen, bar);
;             __builtin_amdgcn_fence(__ATOMIC_ACQUIRE, "agent");
.LBB0_680:
	s_or_b64 exec, exec, s[8:9]
	v_cvt_f32_u32_e32 v4, v2
	s_waitcnt vmcnt(0)
	v_readfirstlane_b32 s3, v3
	v_sub_u32_e32 v3, 0, v2
	v_rcp_iflag_f32_e32 v4, v4
	v_add_u32_e32 v5, s3, v0
	v_mul_f32_e32 v4, 0x4f7ffffe, v4
	v_cvt_u32_f32_e32 v4, v4
	v_mul_lo_u32 v0, v3, v4
	v_mul_hi_u32 v0, v4, v0
	v_add_u32_e32 v0, v4, v0
	v_mul_hi_u32 v0, v5, v0
	v_mul_lo_u32 v3, v0, v2
	v_sub_u32_e32 v3, v5, v3
	v_add_u32_e32 v4, 1, v0
	v_cmp_ge_u32_e32 vcc, v3, v2
	s_nop 1
	v_cndmask_b32_e32 v0, v0, v4, vcc
	v_sub_u32_e32 v4, v3, v2
	v_cndmask_b32_e32 v3, v3, v4, vcc
	v_add_u32_e32 v4, 1, v0
	v_cmp_ge_u32_e32 vcc, v3, v2
	v_add_u32_e32 v3, 1, v5
	s_nop 0
	v_cndmask_b32_e32 v0, v0, v4, vcc
	v_mul_lo_u32 v4, v2, v0
	v_add_u32_e32 v2, v4, v2
	v_cmp_ne_u32_e32 vcc, v3, v2
	s_and_saveexec_b64 s[6:7], vcc
	s_xor_b64 s[6:7], exec, s[6:7]
	s_cbranch_execz .LBB0_694
	buffer_inv sc1
	s_waitcnt lgkmcnt(0)
	v_mul_u32_u24_e32 v4, 7, v1
	v_mov_b32_e32 v2, 0x34e5000

; DI unsigned xb_ld(unsigned* p)              { return __hip_atomic_load(p, __ATOMIC_RELAXED, __HIP_MEMORY_SCOPE_AGENT); }
; DI unsigned xb_add(unsigned* p, unsigned v) { return __hip_atomic_fetch_add(p, v, __ATOMIC_RELAXED, __HIP_MEMORY_SCOPE_AGENT); }
; #define XB_SPIN(cond, bar) do { unsigned _sp = 0; while (cond) { __builtin_amdgcn_s_sleep(1); \
;     if ((++_sp & 255u) == 0u) { if (xb_ld(&(bar)[XB_TMO])) break; if (_sp > XB_SPIN_CAP) { atomicAdd(&(bar)[XB_TMO], 1u); break; } } } } while (0)
; DI void xcd_barrier(unsigned* bar, volatile __attribute__((address_space(3))) unsigned* st) {
;     ...
;             __builtin_amdgcn_fence(__ATOMIC_RELEASE, "agent");
;             asm volatile("s_waitcnt vmcnt(0)" ::: "memory");
;             const unsigned og = xb_add(&bar[XB_TOP], 1u);
;             const unsigned tg = og / nx;
;             if (og + 1u == (tg + 1u) * nx) xb_add(&bar[XB_TOPGEN], 1u);
;             else XB_SPIN(xb_ld(&bar[XB_TOPGEN]) == tg, bar);
;             __builtin_amdgcn_fence(__ATOMIC_ACQUIRE, "agent");
;             xb_add(&bar[XB_XGEN(x)], 1u);
;             asm volatile("s_waitcnt vmcnt(0)" ::: "memory");
;         } else {
;             XB_SPIN(xb_ld(&bar[XB_XGEN(x)]) == gen, bar);
;             __builtin_amdgcn_fence(__ATOMIC_ACQUIRE, "agent");
;             asm volatile("s_waitcnt vmcnt(0)" ::: "memory");
;         }
.Lnlf_d7:
	s_mov_b64 s[8:9], exec
.LBB0_693:
	s_or_b64 exec, exec, s[8:9]
	s_waitcnt vmcnt(0)
	s_waitcnt vmcnt(0)
.LBB0_694:
	s_andn2_saveexec_b64 s[6:7], s[6:7]
	s_cbranch_execz .LBB0_714
	s_mov_b64 s[6:7], exec
	buffer_wbl2 sc1
	s_waitcnt lgkmcnt(0)
	s_waitcnt vmcnt(0)
	v_mov_b32_e32 v2, 0x34e5000
	v_mov_b32_e32 v3, 1
	global_atomic_add v2, v3, s[70:71] offset:1280
	v_mul_u32_u24_e32 v4, 7, v1
	buffer_inv sc1

; DI unsigned xb_ld(unsigned* p)              { return __hip_atomic_load(p, __ATOMIC_RELAXED, __HIP_MEMORY_SCOPE_AGENT); }
; DI unsigned xb_add(unsigned* p, unsigned v) { return __hip_atomic_fetch_add(p, v, __ATOMIC_RELAXED, __HIP_MEMORY_SCOPE_AGENT); }
; #define XB_SPIN(cond, bar) do { unsigned _sp = 0; while (cond) { __builtin_amdgcn_s_sleep(1); \
;     if ((++_sp & 255u) == 0u) { if (xb_ld(&(bar)[XB_TMO])) break; if (_sp > XB_SPIN_CAP) { atomicAdd(&(bar)[XB_TMO], 1u); break; } } } } while (0)
; DI void xcd_barrier(unsigned* bar, volatile __attribute__((address_space(3))) unsigned* st) {
;     ...
;         const unsigned old = xb_add(&bar[XB_XSUB(x)], 1u);
;         const unsigned gen = old / nloc;
;         if (old + 1u == (gen + 1u) * nloc) {
;             __builtin_amdgcn_fence(__ATOMIC_RELEASE, "agent");
;             asm volatile("s_waitcnt vmcnt(0)" ::: "memory");
;             const unsigned og = xb_add(&bar[XB_TOP], 1u);
;             const unsigned tg = og / nx;
;             if (og + 1u == (tg + 1u) * nx) xb_add(&bar[XB_TOPGEN], 1u);
;             else XB_SPIN(xb_ld(&bar[XB_TOPGEN]) == tg, bar);
;             __builtin_amdgcn_fence(__ATOMIC_ACQUIRE, "agent");
;             xb_add(&bar[XB_XGEN(x)], 1u);
;             asm volatile("s_waitcnt vmcnt(0)" ::: "memory");
;         } else {
;             XB_SPIN(xb_ld(&bar[XB_XGEN(x)]) == gen, bar);
;             __builtin_amdgcn_fence(__ATOMIC_ACQUIRE, "agent");
.LBB0_801:
	s_or_b64 exec, exec, s[8:9]
	v_cvt_f32_u32_e32 v4, v2
	s_waitcnt vmcnt(0)
	v_readfirstlane_b32 s3, v3
	v_sub_u32_e32 v3, 0, v2
	v_rcp_iflag_f32_e32 v4, v4
	v_add_u32_e32 v5, s3, v0
	v_mul_f32_e32 v4, 0x4f7ffffe, v4
	v_cvt_u32_f32_e32 v4, v4
	v_mul_lo_u32 v0, v3, v4
	v_mul_hi_u32 v0, v4, v0
	v_add_u32_e32 v0, v4, v0
	v_mul_hi_u32 v0, v5, v0
	v_mul_lo_u32 v3, v0, v2
	v_sub_u32_e32 v3, v5, v3
	v_add_u32_e32 v4, 1, v0
	v_cmp_ge_u32_e32 vcc, v3, v2
	s_nop 1
	v_cndmask_b32_e32 v0, v0, v4, vcc
	v_sub_u32_e32 v4, v3, v2
	v_cndmask_b32_e32 v3, v3, v4, vcc
	v_add_u32_e32 v4, 1, v0
	v_cmp_ge_u32_e32 vcc, v3, v2
	v_add_u32_e32 v3, 1, v5
	s_nop 0
	v_cndmask_b32_e32 v0, v0, v4, vcc
	v_mul_lo_u32 v4, v2, v0
	v_add_u32_e32 v2, v4, v2
	v_cmp_ne_u32_e32 vcc, v3, v2
	s_and_saveexec_b64 s[6:7], vcc
	s_xor_b64 s[6:7], exec, s[6:7]
	s_cbranch_execz .LBB0_815
	buffer_inv sc1
	s_waitcnt lgkmcnt(0)
	v_mul_u32_u24_e32 v4, 8, v1
	v_mov_b32_e32 v2, 0x34e5000

; DI unsigned xb_ld(unsigned* p)              { return __hip_atomic_load(p, __ATOMIC_RELAXED, __HIP_MEMORY_SCOPE_AGENT); }
; DI unsigned xb_add(unsigned* p, unsigned v) { return __hip_atomic_fetch_add(p, v, __ATOMIC_RELAXED, __HIP_MEMORY_SCOPE_AGENT); }
; #define XB_SPIN(cond, bar) do { unsigned _sp = 0; while (cond) { __builtin_amdgcn_s_sleep(1); \
;     if ((++_sp & 255u) == 0u) { if (xb_ld(&(bar)[XB_TMO])) break; if (_sp > XB_SPIN_CAP) { atomicAdd(&(bar)[XB_TMO], 1u); break; } } } } while (0)
; DI void xcd_barrier(unsigned* bar, volatile __attribute__((address_space(3))) unsigned* st) {
;     ...
;             __builtin_amdgcn_fence(__ATOMIC_RELEASE, "agent");
;             asm volatile("s_waitcnt vmcnt(0)" ::: "memory");
;             const unsigned og = xb_add(&bar[XB_TOP], 1u);
;             const unsigned tg = og / nx;
;             if (og + 1u == (tg + 1u) * nx) xb_add(&bar[XB_TOPGEN], 1u);
;             else XB_SPIN(xb_ld(&bar[XB_TOPGEN]) == tg, bar);
;             __builtin_amdgcn_fence(__ATOMIC_ACQUIRE, "agent");
;             xb_add(&bar[XB_XGEN(x)], 1u);
;             asm volatile("s_waitcnt vmcnt(0)" ::: "memory");
;         } else {
;             XB_SPIN(xb_ld(&bar[XB_XGEN(x)]) == gen, bar);
;             __builtin_amdgcn_fence(__ATOMIC_ACQUIRE, "agent");
;             asm volatile("s_waitcnt vmcnt(0)" ::: "memory");
;         }
.Lnlf_d8:
	s_mov_b64 s[8:9], exec
.LBB0_814:
	s_or_b64 exec, exec, s[8:9]
	s_waitcnt vmcnt(0)
	s_waitcnt vmcnt(0)
.LBB0_815:
	s_andn2_saveexec_b64 s[6:7], s[6:7]
	s_cbranch_execz .LBB0_835
	s_mov_b64 s[6:7], exec
	buffer_wbl2 sc1
	s_waitcnt lgkmcnt(0)
	s_waitcnt vmcnt(0)
	v_mov_b32_e32 v2, 0x34e5000
	v_mov_b32_e32 v3, 1
	global_atomic_add v2, v3, s[70:71] offset:1280
	v_mul_u32_u24_e32 v4, 8, v1
	buffer_inv sc1

; DI unsigned xb_ld(unsigned* p)              { return __hip_atomic_load(p, __ATOMIC_RELAXED, __HIP_MEMORY_SCOPE_AGENT); }
; DI unsigned xb_add(unsigned* p, unsigned v) { return __hip_atomic_fetch_add(p, v, __ATOMIC_RELAXED, __HIP_MEMORY_SCOPE_AGENT); }
; #define XB_SPIN(cond, bar) do { unsigned _sp = 0; while (cond) { __builtin_amdgcn_s_sleep(1); \
;     if ((++_sp & 255u) == 0u) { if (xb_ld(&(bar)[XB_TMO])) break; if (_sp > XB_SPIN_CAP) { atomicAdd(&(bar)[XB_TMO], 1u); break; } } } } while (0)
; DI void xcd_barrier(unsigned* bar, volatile __attribute__((address_space(3))) unsigned* st) {
;     ...
;         const unsigned old = xb_add(&bar[XB_XSUB(x)], 1u);
;         const unsigned gen = old / nloc;
;         if (old + 1u == (gen + 1u) * nloc) {
;             __builtin_amdgcn_fence(__ATOMIC_RELEASE, "agent");
;             asm volatile("s_waitcnt vmcnt(0)" ::: "memory");
;             const unsigned og = xb_add(&bar[XB_TOP], 1u);
;             const unsigned tg = og / nx;
;             if (og + 1u == (tg + 1u) * nx) xb_add(&bar[XB_TOPGEN], 1u);
;             else XB_SPIN(xb_ld(&bar[XB_TOPGEN]) == tg, bar);
;             __builtin_amdgcn_fence(__ATOMIC_ACQUIRE, "agent");
;             xb_add(&bar[XB_XGEN(x)], 1u);
;             asm volatile("s_waitcnt vmcnt(0)" ::: "memory");
;         } else {
;             XB_SPIN(xb_ld(&bar[XB_XGEN(x)]) == gen, bar);
;             __builtin_amdgcn_fence(__ATOMIC_ACQUIRE, "agent");
.LBB0_877:
	s_or_b64 exec, exec, s[10:11]
	v_cvt_f32_u32_e32 v4, v2
	s_waitcnt vmcnt(0)
	v_readfirstlane_b32 s3, v3
	v_sub_u32_e32 v3, 0, v2
	v_rcp_iflag_f32_e32 v4, v4
	v_add_u32_e32 v5, s3, v0
	v_mul_f32_e32 v4, 0x4f7ffffe, v4
	v_cvt_u32_f32_e32 v4, v4
	v_mul_lo_u32 v0, v3, v4
	v_mul_hi_u32 v0, v4, v0
	v_add_u32_e32 v0, v4, v0
	v_mul_hi_u32 v0, v5, v0
	v_mul_lo_u32 v3, v0, v2
	v_sub_u32_e32 v3, v5, v3
	v_add_u32_e32 v4, 1, v0
	v_cmp_ge_u32_e32 vcc, v3, v2
	s_nop 1
	v_cndmask_b32_e32 v0, v0, v4, vcc
	v_sub_u32_e32 v4, v3, v2
	v_cndmask_b32_e32 v3, v3, v4, vcc
	v_add_u32_e32 v4, 1, v0
	v_cmp_ge_u32_e32 vcc, v3, v2
	v_add_u32_e32 v3, 1, v5
	s_nop 0
	v_cndmask_b32_e32 v0, v0, v4, vcc
	v_mul_lo_u32 v4, v2, v0
	v_add_u32_e32 v2, v4, v2
	v_cmp_ne_u32_e32 vcc, v3, v2
	s_and_saveexec_b64 s[8:9], vcc
	s_xor_b64 s[8:9], exec, s[8:9]
	s_cbranch_execz .LBB0_891
	buffer_inv sc1
	s_waitcnt lgkmcnt(0)
	v_mul_u32_u24_e32 v4, 9, v1
	v_mov_b32_e32 v2, 0x34e5000

; DI unsigned xb_ld(unsigned* p)              { return __hip_atomic_load(p, __ATOMIC_RELAXED, __HIP_MEMORY_SCOPE_AGENT); }
; DI unsigned xb_add(unsigned* p, unsigned v) { return __hip_atomic_fetch_add(p, v, __ATOMIC_RELAXED, __HIP_MEMORY_SCOPE_AGENT); }
; #define XB_SPIN(cond, bar) do { unsigned _sp = 0; while (cond) { __builtin_amdgcn_s_sleep(1); \
;     if ((++_sp & 255u) == 0u) { if (xb_ld(&(bar)[XB_TMO])) break; if (_sp > XB_SPIN_CAP) { atomicAdd(&(bar)[XB_TMO], 1u); break; } } } } while (0)
; DI void xcd_barrier(unsigned* bar, volatile __attribute__((address_space(3))) unsigned* st) {
;     ...
;             __builtin_amdgcn_fence(__ATOMIC_RELEASE, "agent");
;             asm volatile("s_waitcnt vmcnt(0)" ::: "memory");
;             const unsigned og = xb_add(&bar[XB_TOP], 1u);
;             const unsigned tg = og / nx;
;             if (og + 1u == (tg + 1u) * nx) xb_add(&bar[XB_TOPGEN], 1u);
;             else XB_SPIN(xb_ld(&bar[XB_TOPGEN]) == tg, bar);
;             __builtin_amdgcn_fence(__ATOMIC_ACQUIRE, "agent");
.LBB0_891:
	s_andn2_saveexec_b64 s[8:9], s[8:9]
	s_cbranch_execz .LBB0_911
	s_mov_b64 s[8:9], exec
	buffer_wbl2 sc1
	s_waitcnt lgkmcnt(0)
	s_waitcnt vmcnt(0)
	v_mov_b32_e32 v2, 0x34e5000
	v_mov_b32_e32 v3, 1
	global_atomic_add v2, v3, s[70:71] offset:1280
	v_mul_u32_u24_e32 v4, 9, v1
	buffer_inv sc1

; DI unsigned xb_ld(unsigned* p)              { return __hip_atomic_load(p, __ATOMIC_RELAXED, __HIP_MEMORY_SCOPE_AGENT); }
; DI unsigned xb_add(unsigned* p, unsigned v) { return __hip_atomic_fetch_add(p, v, __ATOMIC_RELAXED, __HIP_MEMORY_SCOPE_AGENT); }
; #define XB_SPIN(cond, bar) do { unsigned _sp = 0; while (cond) { __builtin_amdgcn_s_sleep(1); \
;     if ((++_sp & 255u) == 0u) { if (xb_ld(&(bar)[XB_TMO])) break; if (_sp > XB_SPIN_CAP) { atomicAdd(&(bar)[XB_TMO], 1u); break; } } } } while (0)
; DI void xcd_barrier(unsigned* bar, volatile __attribute__((address_space(3))) unsigned* st) {
;     ...
;         const unsigned old = xb_add(&bar[XB_XSUB(x)], 1u);
;         const unsigned gen = old / nloc;
;         if (old + 1u == (gen + 1u) * nloc) {
;             __builtin_amdgcn_fence(__ATOMIC_RELEASE, "agent");
;             asm volatile("s_waitcnt vmcnt(0)" ::: "memory");
;             const unsigned og = xb_add(&bar[XB_TOP], 1u);
;             const unsigned tg = og / nx;
;             if (og + 1u == (tg + 1u) * nx) xb_add(&bar[XB_TOPGEN], 1u);
;             else XB_SPIN(xb_ld(&bar[XB_TOPGEN]) == tg, bar);
;             __builtin_amdgcn_fence(__ATOMIC_ACQUIRE, "agent");
;             xb_add(&bar[XB_XGEN(x)], 1u);
;             asm volatile("s_waitcnt vmcnt(0)" ::: "memory");
;         } else {
;             XB_SPIN(xb_ld(&bar[XB_XGEN(x)]) == gen, bar);
;             __builtin_amdgcn_fence(__ATOMIC_ACQUIRE, "agent");
.LBB0_953:
	s_or_b64 exec, exec, s[10:11]
	v_cvt_f32_u32_e32 v4, v2
	s_waitcnt vmcnt(0)
	v_readfirstlane_b32 s3, v3
	v_sub_u32_e32 v3, 0, v2
	v_rcp_iflag_f32_e32 v4, v4
	v_add_u32_e32 v5, s3, v0
	v_mul_f32_e32 v4, 0x4f7ffffe, v4
	v_cvt_u32_f32_e32 v4, v4
	v_mul_lo_u32 v0, v3, v4
	v_mul_hi_u32 v0, v4, v0
	v_add_u32_e32 v0, v4, v0
	v_mul_hi_u32 v0, v5, v0
	v_mul_lo_u32 v3, v0, v2
	v_sub_u32_e32 v3, v5, v3
	v_add_u32_e32 v4, 1, v0
	v_cmp_ge_u32_e32 vcc, v3, v2
	s_nop 1
	v_cndmask_b32_e32 v0, v0, v4, vcc
	v_sub_u32_e32 v4, v3, v2
	v_cndmask_b32_e32 v3, v3, v4, vcc
	v_add_u32_e32 v4, 1, v0
	v_cmp_ge_u32_e32 vcc, v3, v2
	v_add_u32_e32 v3, 1, v5
	s_nop 0
	v_cndmask_b32_e32 v0, v0, v4, vcc
	v_mul_lo_u32 v4, v2, v0
	v_add_u32_e32 v2, v4, v2
	v_cmp_ne_u32_e32 vcc, v3, v2
	s_and_saveexec_b64 s[8:9], vcc
	s_xor_b64 s[8:9], exec, s[8:9]
	s_cbranch_execz .LBB0_967
	buffer_inv sc1
	s_waitcnt lgkmcnt(0)
	v_mul_u32_u24_e32 v4, 10, v1
	v_mov_b32_e32 v2, 0x34e5000

; DI unsigned xb_ld(unsigned* p)              { return __hip_atomic_load(p, __ATOMIC_RELAXED, __HIP_MEMORY_SCOPE_AGENT); }
; DI unsigned xb_add(unsigned* p, unsigned v) { return __hip_atomic_fetch_add(p, v, __ATOMIC_RELAXED, __HIP_MEMORY_SCOPE_AGENT); }
; #define XB_SPIN(cond, bar) do { unsigned _sp = 0; while (cond) { __builtin_amdgcn_s_sleep(1); \
;     if ((++_sp & 255u) == 0u) { if (xb_ld(&(bar)[XB_TMO])) break; if (_sp > XB_SPIN_CAP) { atomicAdd(&(bar)[XB_TMO], 1u); break; } } } } while (0)
; DI void xcd_barrier(unsigned* bar, volatile __attribute__((address_space(3))) unsigned* st) {
;     ...
;             __builtin_amdgcn_fence(__ATOMIC_RELEASE, "agent");
;             asm volatile("s_waitcnt vmcnt(0)" ::: "memory");
;             const unsigned og = xb_add(&bar[XB_TOP], 1u);
;             const unsigned tg = og / nx;
;             if (og + 1u == (tg + 1u) * nx) xb_add(&bar[XB_TOPGEN], 1u);
;             else XB_SPIN(xb_ld(&bar[XB_TOPGEN]) == tg, bar);
;             __builtin_amdgcn_fence(__ATOMIC_ACQUIRE, "agent");
.LBB0_967:
	s_andn2_saveexec_b64 s[8:9], s[8:9]
	s_cbranch_execz .LBB0_987
	s_mov_b64 s[8:9], exec
	buffer_wbl2 sc1
	s_waitcnt lgkmcnt(0)
	s_waitcnt vmcnt(0)
	v_mov_b32_e32 v2, 0x34e5000
	v_mov_b32_e32 v3, 1
	global_atomic_add v2, v3, s[70:71] offset:1280
	v_mul_u32_u24_e32 v4, 10, v1
	buffer_inv sc1

; DI unsigned xb_ld(unsigned* p)              { return __hip_atomic_load(p, __ATOMIC_RELAXED, __HIP_MEMORY_SCOPE_AGENT); }
; DI unsigned xb_add(unsigned* p, unsigned v) { return __hip_atomic_fetch_add(p, v, __ATOMIC_RELAXED, __HIP_MEMORY_SCOPE_AGENT); }
; #define XB_SPIN(cond, bar) do { unsigned _sp = 0; while (cond) { __builtin_amdgcn_s_sleep(1); \
;     if ((++_sp & 255u) == 0u) { if (xb_ld(&(bar)[XB_TMO])) break; if (_sp > XB_SPIN_CAP) { atomicAdd(&(bar)[XB_TMO], 1u); break; } } } } while (0)
; DI void xcd_barrier(unsigned* bar, volatile __attribute__((address_space(3))) unsigned* st) {
;     ...
;         const unsigned old = xb_add(&bar[XB_XSUB(x)], 1u);
;         const unsigned gen = old / nloc;
;         if (old + 1u == (gen + 1u) * nloc) {
;             __builtin_amdgcn_fence(__ATOMIC_RELEASE, "agent");
;             asm volatile("s_waitcnt vmcnt(0)" ::: "memory");
;             const unsigned og = xb_add(&bar[XB_TOP], 1u);
;             const unsigned tg = og / nx;
;             if (og + 1u == (tg + 1u) * nx) xb_add(&bar[XB_TOPGEN], 1u);
;             else XB_SPIN(xb_ld(&bar[XB_TOPGEN]) == tg, bar);
;             __builtin_amdgcn_fence(__ATOMIC_ACQUIRE, "agent");
;             xb_add(&bar[XB_XGEN(x)], 1u);
;             asm volatile("s_waitcnt vmcnt(0)" ::: "memory");
;         } else {
;             XB_SPIN(xb_ld(&bar[XB_XGEN(x)]) == gen, bar);
;             __builtin_amdgcn_fence(__ATOMIC_ACQUIRE, "agent");
.LBB0_1016:
	s_or_b64 exec, exec, s[12:13]
	v_cvt_f32_u32_e32 v4, v2
	s_waitcnt vmcnt(0)
	v_readfirstlane_b32 s3, v3
	v_sub_u32_e32 v3, 0, v2
	v_rcp_iflag_f32_e32 v4, v4
	v_add_u32_e32 v5, s3, v0
	v_mul_f32_e32 v4, 0x4f7ffffe, v4
	v_cvt_u32_f32_e32 v4, v4
	v_mul_lo_u32 v0, v3, v4
	v_mul_hi_u32 v0, v4, v0
	v_add_u32_e32 v0, v4, v0
	v_mul_hi_u32 v0, v5, v0
	v_mul_lo_u32 v3, v0, v2
	v_sub_u32_e32 v3, v5, v3
	v_add_u32_e32 v4, 1, v0
	v_cmp_ge_u32_e32 vcc, v3, v2
	s_nop 1
	v_cndmask_b32_e32 v0, v0, v4, vcc
	v_sub_u32_e32 v4, v3, v2
	v_cndmask_b32_e32 v3, v3, v4, vcc
	v_add_u32_e32 v4, 1, v0
	v_cmp_ge_u32_e32 vcc, v3, v2
	v_add_u32_e32 v3, 1, v5
	s_nop 0
	v_cndmask_b32_e32 v0, v0, v4, vcc
	v_mul_lo_u32 v4, v2, v0
	v_add_u32_e32 v2, v4, v2
	v_cmp_ne_u32_e32 vcc, v3, v2
	s_and_saveexec_b64 s[8:9], vcc
	s_xor_b64 s[8:9], exec, s[8:9]
	s_cbranch_execz .LBB0_1030
	buffer_inv sc1
	s_waitcnt lgkmcnt(0)
	v_mul_u32_u24_e32 v4, 11, v1
	v_mov_b32_e32 v2, 0x34e5000

; DI unsigned xb_ld(unsigned* p)              { return __hip_atomic_load(p, __ATOMIC_RELAXED, __HIP_MEMORY_SCOPE_AGENT); }
; #define XB_SPIN(cond, bar) do { unsigned _sp = 0; while (cond) { __builtin_amdgcn_s_sleep(1); \
;     if ((++_sp & 255u) == 0u) { if (xb_ld(&(bar)[XB_TMO])) break; if (_sp > XB_SPIN_CAP) { atomicAdd(&(bar)[XB_TMO], 1u); break; } } } } while (0)
; DI void xcd_barrier(unsigned* bar, volatile __attribute__((address_space(3))) unsigned* st) {
;     ...
;             XB_SPIN(xb_ld(&bar[XB_XGEN(x)]) == gen, bar);
;             __builtin_amdgcn_fence(__ATOMIC_ACQUIRE, "agent");
;             asm volatile("s_waitcnt vmcnt(0)" ::: "memory");
;         }
.Lnlf_d11:
	s_mov_b64 s[12:13], exec

; DI unsigned xb_ld(unsigned* p)              { return __hip_atomic_load(p, __ATOMIC_RELAXED, __HIP_MEMORY_SCOPE_AGENT); }
; DI unsigned xb_add(unsigned* p, unsigned v) { return __hip_atomic_fetch_add(p, v, __ATOMIC_RELAXED, __HIP_MEMORY_SCOPE_AGENT); }
; #define XB_SPIN(cond, bar) do { unsigned _sp = 0; while (cond) { __builtin_amdgcn_s_sleep(1); \
;     if ((++_sp & 255u) == 0u) { if (xb_ld(&(bar)[XB_TMO])) break; if (_sp > XB_SPIN_CAP) { atomicAdd(&(bar)[XB_TMO], 1u); break; } } } } while (0)
; DI void xcd_barrier(unsigned* bar, volatile __attribute__((address_space(3))) unsigned* st) {
;     ...
;             __builtin_amdgcn_fence(__ATOMIC_RELEASE, "agent");
;             asm volatile("s_waitcnt vmcnt(0)" ::: "memory");
;             const unsigned og = xb_add(&bar[XB_TOP], 1u);
;             const unsigned tg = og / nx;
;             if (og + 1u == (tg + 1u) * nx) xb_add(&bar[XB_TOPGEN], 1u);
;             else XB_SPIN(xb_ld(&bar[XB_TOPGEN]) == tg, bar);
;             __builtin_amdgcn_fence(__ATOMIC_ACQUIRE, "agent");
.LBB0_1030:
	s_andn2_saveexec_b64 s[8:9], s[8:9]
	s_cbranch_execz .LBB0_1050
	s_mov_b64 s[8:9], exec
	buffer_wbl2 sc1
	s_waitcnt lgkmcnt(0)
	s_waitcnt vmcnt(0)
	v_mov_b32_e32 v2, 0x34e5000
	v_mov_b32_e32 v3, 1
	global_atomic_add v2, v3, s[70:71] offset:1280
	v_mul_u32_u24_e32 v4, 11, v1
	buffer_inv sc1

; DI unsigned xb_add(unsigned* p, unsigned v) { return __hip_atomic_fetch_add(p, v, __ATOMIC_RELAXED, __HIP_MEMORY_SCOPE_AGENT); }
; DI void xcd_barrier(unsigned* bar, volatile __attribute__((address_space(3))) unsigned* st) {
;     ...
;             __builtin_amdgcn_fence(__ATOMIC_ACQUIRE, "agent");
;             xb_add(&bar[XB_XGEN(x)], 1u);
;             asm volatile("s_waitcnt vmcnt(0)" ::: "memory");
.LBB0_1047:
	s_or_b64 exec, exec, s[8:9]
	s_mov_b64 s[8:9], exec
	v_mbcnt_lo_u32_b32 v0, s8, 0
	v_mbcnt_hi_u32_b32 v0, s9, v0
	v_cmp_eq_u32_e32 vcc, 0, v0
	s_and_saveexec_b64 s[12:13], vcc
	s_cbranch_execz .LBB0_1049

; DI unsigned xb_ld(unsigned* p)              { return __hip_atomic_load(p, __ATOMIC_RELAXED, __HIP_MEMORY_SCOPE_AGENT); }
; DI unsigned xb_add(unsigned* p, unsigned v) { return __hip_atomic_fetch_add(p, v, __ATOMIC_RELAXED, __HIP_MEMORY_SCOPE_AGENT); }
; #define XB_SPIN(cond, bar) do { unsigned _sp = 0; while (cond) { __builtin_amdgcn_s_sleep(1); \
;     if ((++_sp & 255u) == 0u) { if (xb_ld(&(bar)[XB_TMO])) break; if (_sp > XB_SPIN_CAP) { atomicAdd(&(bar)[XB_TMO], 1u); break; } } } } while (0)
; DI void xcd_barrier(unsigned* bar, volatile __attribute__((address_space(3))) unsigned* st) {
;     ...
;         const unsigned old = xb_add(&bar[XB_XSUB(x)], 1u);
;         const unsigned gen = old / nloc;
;         if (old + 1u == (gen + 1u) * nloc) {
;             __builtin_amdgcn_fence(__ATOMIC_RELEASE, "agent");
;             asm volatile("s_waitcnt vmcnt(0)" ::: "memory");
;             const unsigned og = xb_add(&bar[XB_TOP], 1u);
;             const unsigned tg = og / nx;
;             if (og + 1u == (tg + 1u) * nx) xb_add(&bar[XB_TOPGEN], 1u);
;             else XB_SPIN(xb_ld(&bar[XB_TOPGEN]) == tg, bar);
;             __builtin_amdgcn_fence(__ATOMIC_ACQUIRE, "agent");
;             xb_add(&bar[XB_XGEN(x)], 1u);
;             asm volatile("s_waitcnt vmcnt(0)" ::: "memory");
;         } else {
;             XB_SPIN(xb_ld(&bar[XB_XGEN(x)]) == gen, bar);
;             __builtin_amdgcn_fence(__ATOMIC_ACQUIRE, "agent");
.LBB0_1110:
	s_or_b64 exec, exec, s[16:17]
	v_cvt_f32_u32_e32 v4, v2
	s_waitcnt vmcnt(0)
	v_readfirstlane_b32 s3, v3
	v_sub_u32_e32 v3, 0, v2
	v_rcp_iflag_f32_e32 v4, v4
	v_add_u32_e32 v5, s3, v0
	v_mul_f32_e32 v4, 0x4f7ffffe, v4
	v_cvt_u32_f32_e32 v4, v4
	v_mul_lo_u32 v0, v3, v4
	v_mul_hi_u32 v0, v4, v0
	v_add_u32_e32 v0, v4, v0
	v_mul_hi_u32 v0, v5, v0
	v_mul_lo_u32 v3, v0, v2
	v_sub_u32_e32 v3, v5, v3
	v_add_u32_e32 v4, 1, v0
	v_cmp_ge_u32_e32 vcc, v3, v2
	s_nop 1
	v_cndmask_b32_e32 v0, v0, v4, vcc
	v_sub_u32_e32 v4, v3, v2
	v_cndmask_b32_e32 v3, v3, v4, vcc
	v_add_u32_e32 v4, 1, v0
	v_cmp_ge_u32_e32 vcc, v3, v2
	v_add_u32_e32 v3, 1, v5
	s_nop 0
	v_cndmask_b32_e32 v0, v0, v4, vcc
	v_mul_lo_u32 v4, v2, v0
	v_add_u32_e32 v2, v4, v2
	v_cmp_ne_u32_e32 vcc, v3, v2
	s_and_saveexec_b64 s[8:9], vcc
	s_xor_b64 s[8:9], exec, s[8:9]
	s_cbranch_execz .LBB0_1124
	buffer_inv sc1
	s_waitcnt lgkmcnt(0)
	v_mul_u32_u24_e32 v4, 12, v1
	v_mov_b32_e32 v2, 0x34e5000

; DI unsigned xb_ld(unsigned* p)              { return __hip_atomic_load(p, __ATOMIC_RELAXED, __HIP_MEMORY_SCOPE_AGENT); }
; #define XB_SPIN(cond, bar) do { unsigned _sp = 0; while (cond) { __builtin_amdgcn_s_sleep(1); \
;     if ((++_sp & 255u) == 0u) { if (xb_ld(&(bar)[XB_TMO])) break; if (_sp > XB_SPIN_CAP) { atomicAdd(&(bar)[XB_TMO], 1u); break; } } } } while (0)
; DI void xcd_barrier(unsigned* bar, volatile __attribute__((address_space(3))) unsigned* st) {
;     ...
;             XB_SPIN(xb_ld(&bar[XB_XGEN(x)]) == gen, bar);
;             __builtin_amdgcn_fence(__ATOMIC_ACQUIRE, "agent");
;             asm volatile("s_waitcnt vmcnt(0)" ::: "memory");
;         }
.Lnlf_d12:
	s_mov_b64 s[16:17], exec

; DI unsigned xb_ld(unsigned* p)              { return __hip_atomic_load(p, __ATOMIC_RELAXED, __HIP_MEMORY_SCOPE_AGENT); }
; DI unsigned xb_add(unsigned* p, unsigned v) { return __hip_atomic_fetch_add(p, v, __ATOMIC_RELAXED, __HIP_MEMORY_SCOPE_AGENT); }
; #define XB_SPIN(cond, bar) do { unsigned _sp = 0; while (cond) { __builtin_amdgcn_s_sleep(1); \
;     if ((++_sp & 255u) == 0u) { if (xb_ld(&(bar)[XB_TMO])) break; if (_sp > XB_SPIN_CAP) { atomicAdd(&(bar)[XB_TMO], 1u); break; } } } } while (0)
; DI void xcd_barrier(unsigned* bar, volatile __attribute__((address_space(3))) unsigned* st) {
;     ...
;             __builtin_amdgcn_fence(__ATOMIC_RELEASE, "agent");
;             asm volatile("s_waitcnt vmcnt(0)" ::: "memory");
;             const unsigned og = xb_add(&bar[XB_TOP], 1u);
;             const unsigned tg = og / nx;
;             if (og + 1u == (tg + 1u) * nx) xb_add(&bar[XB_TOPGEN], 1u);
;             else XB_SPIN(xb_ld(&bar[XB_TOPGEN]) == tg, bar);
;             __builtin_amdgcn_fence(__ATOMIC_ACQUIRE, "agent");
.LBB0_1124:
	s_andn2_saveexec_b64 s[8:9], s[8:9]
	s_cbranch_execz .LBB0_1144
	s_mov_b64 s[8:9], exec
	buffer_wbl2 sc1
	s_waitcnt lgkmcnt(0)
	s_waitcnt vmcnt(0)
	v_mov_b32_e32 v2, 0x34e5000
	v_mov_b32_e32 v3, 1
	global_atomic_add v2, v3, s[70:71] offset:1280
	v_mul_u32_u24_e32 v4, 12, v1
	buffer_inv sc1

; DI unsigned xb_add(unsigned* p, unsigned v) { return __hip_atomic_fetch_add(p, v, __ATOMIC_RELAXED, __HIP_MEMORY_SCOPE_AGENT); }
; DI void xcd_barrier(unsigned* bar, volatile __attribute__((address_space(3))) unsigned* st) {
;     ...
;             __builtin_amdgcn_fence(__ATOMIC_ACQUIRE, "agent");
;             xb_add(&bar[XB_XGEN(x)], 1u);
;             asm volatile("s_waitcnt vmcnt(0)" ::: "memory");
.LBB0_1141:
	s_or_b64 exec, exec, s[8:9]
	s_mov_b64 s[8:9], exec
	v_mbcnt_lo_u32_b32 v0, s8, 0
	v_mbcnt_hi_u32_b32 v0, s9, v0
	v_cmp_eq_u32_e32 vcc, 0, v0
	s_and_saveexec_b64 s[16:17], vcc
	s_cbranch_execz .LBB0_1143

; DI unsigned xb_ld(unsigned* p)              { return __hip_atomic_load(p, __ATOMIC_RELAXED, __HIP_MEMORY_SCOPE_AGENT); }
; DI unsigned xb_add(unsigned* p, unsigned v) { return __hip_atomic_fetch_add(p, v, __ATOMIC_RELAXED, __HIP_MEMORY_SCOPE_AGENT); }
; #define XB_SPIN(cond, bar) do { unsigned _sp = 0; while (cond) { __builtin_amdgcn_s_sleep(1); \
;     if ((++_sp & 255u) == 0u) { if (xb_ld(&(bar)[XB_TMO])) break; if (_sp > XB_SPIN_CAP) { atomicAdd(&(bar)[XB_TMO], 1u); break; } } } } while (0)
; DI void xcd_barrier(unsigned* bar, volatile __attribute__((address_space(3))) unsigned* st) {
;     ...
;         const unsigned old = xb_add(&bar[XB_XSUB(x)], 1u);
;         const unsigned gen = old / nloc;
;         if (old + 1u == (gen + 1u) * nloc) {
;             __builtin_amdgcn_fence(__ATOMIC_RELEASE, "agent");
;             asm volatile("s_waitcnt vmcnt(0)" ::: "memory");
;             const unsigned og = xb_add(&bar[XB_TOP], 1u);
;             const unsigned tg = og / nx;
;             if (og + 1u == (tg + 1u) * nx) xb_add(&bar[XB_TOPGEN], 1u);
;             else XB_SPIN(xb_ld(&bar[XB_TOPGEN]) == tg, bar);
;             __builtin_amdgcn_fence(__ATOMIC_ACQUIRE, "agent");
;             xb_add(&bar[XB_XGEN(x)], 1u);
;             asm volatile("s_waitcnt vmcnt(0)" ::: "memory");
;         } else {
;             XB_SPIN(xb_ld(&bar[XB_XGEN(x)]) == gen, bar);
;             __builtin_amdgcn_fence(__ATOMIC_ACQUIRE, "agent");
.LBB0_1169:
	s_or_b64 exec, exec, s[12:13]
	v_cvt_f32_u32_e32 v4, v2
	s_waitcnt vmcnt(0)
	v_readfirstlane_b32 s3, v3
	v_sub_u32_e32 v3, 0, v2
	v_rcp_iflag_f32_e32 v4, v4
	v_add_u32_e32 v5, s3, v0
	v_mul_f32_e32 v4, 0x4f7ffffe, v4
	v_cvt_u32_f32_e32 v4, v4
	v_mul_lo_u32 v0, v3, v4
	v_mul_hi_u32 v0, v4, v0
	v_add_u32_e32 v0, v4, v0
	v_mul_hi_u32 v0, v5, v0
	v_mul_lo_u32 v3, v0, v2
	v_sub_u32_e32 v3, v5, v3
	v_add_u32_e32 v4, 1, v0
	v_cmp_ge_u32_e32 vcc, v3, v2
	s_nop 1
	v_cndmask_b32_e32 v0, v0, v4, vcc
	v_sub_u32_e32 v4, v3, v2
	v_cndmask_b32_e32 v3, v3, v4, vcc
	v_add_u32_e32 v4, 1, v0
	v_cmp_ge_u32_e32 vcc, v3, v2
	v_add_u32_e32 v3, 1, v5
	s_nop 0
	v_cndmask_b32_e32 v0, v0, v4, vcc
	v_mul_lo_u32 v4, v2, v0
	v_add_u32_e32 v2, v4, v2
	v_cmp_ne_u32_e32 vcc, v3, v2
	s_and_saveexec_b64 s[8:9], vcc
	s_xor_b64 s[8:9], exec, s[8:9]
	s_cbranch_execz .LBB0_1183
	buffer_inv sc1
	s_waitcnt lgkmcnt(0)
	v_mul_u32_u24_e32 v4, 13, v1
	v_mov_b32_e32 v2, 0x34e5000

; DI unsigned xb_ld(unsigned* p)              { return __hip_atomic_load(p, __ATOMIC_RELAXED, __HIP_MEMORY_SCOPE_AGENT); }
; DI unsigned xb_add(unsigned* p, unsigned v) { return __hip_atomic_fetch_add(p, v, __ATOMIC_RELAXED, __HIP_MEMORY_SCOPE_AGENT); }
; #define XB_SPIN(cond, bar) do { unsigned _sp = 0; while (cond) { __builtin_amdgcn_s_sleep(1); \
;     if ((++_sp & 255u) == 0u) { if (xb_ld(&(bar)[XB_TMO])) break; if (_sp > XB_SPIN_CAP) { atomicAdd(&(bar)[XB_TMO], 1u); break; } } } } while (0)
; DI void xcd_barrier(unsigned* bar, volatile __attribute__((address_space(3))) unsigned* st) {
;     ...
;             __builtin_amdgcn_fence(__ATOMIC_RELEASE, "agent");
;             asm volatile("s_waitcnt vmcnt(0)" ::: "memory");
;             const unsigned og = xb_add(&bar[XB_TOP], 1u);
;             const unsigned tg = og / nx;
;             if (og + 1u == (tg + 1u) * nx) xb_add(&bar[XB_TOPGEN], 1u);
;             else XB_SPIN(xb_ld(&bar[XB_TOPGEN]) == tg, bar);
;             __builtin_amdgcn_fence(__ATOMIC_ACQUIRE, "agent");
.LBB0_1183:
	s_andn2_saveexec_b64 s[8:9], s[8:9]
	s_cbranch_execz .LBB0_1203
	s_mov_b64 s[8:9], exec
	buffer_wbl2 sc1
	s_waitcnt lgkmcnt(0)
	s_waitcnt vmcnt(0)
	v_mov_b32_e32 v2, 0x34e5000
	v_mov_b32_e32 v3, 1
	global_atomic_add v2, v3, s[70:71] offset:1280
	v_mul_u32_u24_e32 v4, 13, v1
	buffer_inv sc1

; DI unsigned xb_ld(unsigned* p)              { return __hip_atomic_load(p, __ATOMIC_RELAXED, __HIP_MEMORY_SCOPE_AGENT); }
; DI unsigned xb_add(unsigned* p, unsigned v) { return __hip_atomic_fetch_add(p, v, __ATOMIC_RELAXED, __HIP_MEMORY_SCOPE_AGENT); }
; #define XB_SPIN(cond, bar) do { unsigned _sp = 0; while (cond) { __builtin_amdgcn_s_sleep(1); \
;     if ((++_sp & 255u) == 0u) { if (xb_ld(&(bar)[XB_TMO])) break; if (_sp > XB_SPIN_CAP) { atomicAdd(&(bar)[XB_TMO], 1u); break; } } } } while (0)
; DI void xcd_barrier(unsigned* bar, volatile __attribute__((address_space(3))) unsigned* st) {
;     ...
;         const unsigned old = xb_add(&bar[XB_XSUB(x)], 1u);
;         const unsigned gen = old / nloc;
;         if (old + 1u == (gen + 1u) * nloc) {
;             __builtin_amdgcn_fence(__ATOMIC_RELEASE, "agent");
;             asm volatile("s_waitcnt vmcnt(0)" ::: "memory");
;             const unsigned og = xb_add(&bar[XB_TOP], 1u);
;             const unsigned tg = og / nx;
;             if (og + 1u == (tg + 1u) * nx) xb_add(&bar[XB_TOPGEN], 1u);
;             else XB_SPIN(xb_ld(&bar[XB_TOPGEN]) == tg, bar);
;             __builtin_amdgcn_fence(__ATOMIC_ACQUIRE, "agent");
;             xb_add(&bar[XB_XGEN(x)], 1u);
;             asm volatile("s_waitcnt vmcnt(0)" ::: "memory");
;         } else {
;             XB_SPIN(xb_ld(&bar[XB_XGEN(x)]) == gen, bar);
;             __builtin_amdgcn_fence(__ATOMIC_ACQUIRE, "agent");
.LBB0_1249:
	s_or_b64 exec, exec, s[6:7]
	v_cvt_f32_u32_e32 v4, v2
	s_waitcnt vmcnt(0)
	v_readfirstlane_b32 s4, v3
	v_sub_u32_e32 v3, 0, v2
	v_rcp_iflag_f32_e32 v4, v4
	v_add_u32_e32 v5, s4, v0
	v_mul_f32_e32 v4, 0x4f7ffffe, v4
	v_cvt_u32_f32_e32 v4, v4
	v_mul_lo_u32 v0, v3, v4
	v_mul_hi_u32 v0, v4, v0
	v_add_u32_e32 v0, v4, v0
	v_mul_hi_u32 v0, v5, v0
	v_mul_lo_u32 v3, v0, v2
	v_sub_u32_e32 v3, v5, v3
	v_add_u32_e32 v4, 1, v0
	v_cmp_ge_u32_e32 vcc, v3, v2
	s_nop 1
	v_cndmask_b32_e32 v0, v0, v4, vcc
	v_sub_u32_e32 v4, v3, v2
	v_cndmask_b32_e32 v3, v3, v4, vcc
	v_add_u32_e32 v4, 1, v0
	v_cmp_ge_u32_e32 vcc, v3, v2
	v_add_u32_e32 v3, 1, v5
	s_nop 0
	v_cndmask_b32_e32 v0, v0, v4, vcc
	v_mul_lo_u32 v4, v2, v0
	v_add_u32_e32 v2, v4, v2
	v_cmp_ne_u32_e32 vcc, v3, v2
	s_and_saveexec_b64 s[4:5], vcc
	s_xor_b64 s[4:5], exec, s[4:5]
	s_cbranch_execz .LBB0_1263
	buffer_inv sc1
	s_waitcnt lgkmcnt(0)
	v_mul_u32_u24_e32 v4, 14, v1
	v_mov_b32_e32 v2, 0x34e5000

; DI unsigned xb_ld(unsigned* p)              { return __hip_atomic_load(p, __ATOMIC_RELAXED, __HIP_MEMORY_SCOPE_AGENT); }
; DI unsigned xb_add(unsigned* p, unsigned v) { return __hip_atomic_fetch_add(p, v, __ATOMIC_RELAXED, __HIP_MEMORY_SCOPE_AGENT); }
; #define XB_SPIN(cond, bar) do { unsigned _sp = 0; while (cond) { __builtin_amdgcn_s_sleep(1); \
;     if ((++_sp & 255u) == 0u) { if (xb_ld(&(bar)[XB_TMO])) break; if (_sp > XB_SPIN_CAP) { atomicAdd(&(bar)[XB_TMO], 1u); break; } } } } while (0)
; DI void xcd_barrier(unsigned* bar, volatile __attribute__((address_space(3))) unsigned* st) {
;     ...
;             __builtin_amdgcn_fence(__ATOMIC_RELEASE, "agent");
;             asm volatile("s_waitcnt vmcnt(0)" ::: "memory");
;             const unsigned og = xb_add(&bar[XB_TOP], 1u);
;             const unsigned tg = og / nx;
;             if (og + 1u == (tg + 1u) * nx) xb_add(&bar[XB_TOPGEN], 1u);
;             else XB_SPIN(xb_ld(&bar[XB_TOPGEN]) == tg, bar);
;             __builtin_amdgcn_fence(__ATOMIC_ACQUIRE, "agent");
;             xb_add(&bar[XB_XGEN(x)], 1u);
;             asm volatile("s_waitcnt vmcnt(0)" ::: "memory");
;         } else {
;             XB_SPIN(xb_ld(&bar[XB_XGEN(x)]) == gen, bar);
;             __builtin_amdgcn_fence(__ATOMIC_ACQUIRE, "agent");
;             asm volatile("s_waitcnt vmcnt(0)" ::: "memory");
;         }
.Lnlf_d14:
	s_mov_b64 s[6:7], exec
.LBB0_1262:
	s_or_b64 exec, exec, s[6:7]
	s_waitcnt vmcnt(0)
	s_waitcnt vmcnt(0)
.LBB0_1263:
	s_andn2_saveexec_b64 s[4:5], s[4:5]
	s_cbranch_execz .LBB0_1283
	s_mov_b64 s[4:5], exec
	buffer_wbl2 sc1
	s_waitcnt lgkmcnt(0)
	s_waitcnt vmcnt(0)
	v_mov_b32_e32 v2, 0x34e5000
	v_mov_b32_e32 v3, 1
	global_atomic_add v2, v3, s[70:71] offset:1280
	v_mul_u32_u24_e32 v4, 14, v1
	buffer_inv sc1

; DI unsigned xb_add(unsigned* p, unsigned v) { return __hip_atomic_fetch_add(p, v, __ATOMIC_RELAXED, __HIP_MEMORY_SCOPE_AGENT); }
; DI void xcd_barrier(unsigned* bar, volatile __attribute__((address_space(3))) unsigned* st) {
;     ...
;             __builtin_amdgcn_fence(__ATOMIC_ACQUIRE, "agent");
;             xb_add(&bar[XB_XGEN(x)], 1u);
;             asm volatile("s_waitcnt vmcnt(0)" ::: "memory");
.LBB0_1280:
	s_or_b64 exec, exec, s[4:5]
	s_mov_b64 s[4:5], exec
	v_mbcnt_lo_u32_b32 v0, s4, 0
	v_mbcnt_hi_u32_b32 v0, s5, v0
	v_cmp_eq_u32_e32 vcc, 0, v0
	s_and_saveexec_b64 s[6:7], vcc
	s_cbranch_execz .LBB0_1282
